# strategy 8 on the GLA scan: 20 fragments of a 4-step batch read up front (state-independent), counted lgkmcnt per step
# speedup vs baseline: 1.0038x; 1.0038x over previous
; DI unsigned pk2(float lo, float hi) { return pg8::cvt_pk_bf16(lo, hi); }
; DI f32x4 mfma16(bf16x8 a, bf16x8 b, f32x4 c) { return __builtin_amdgcn_mfma_f32_16x16x32_bf16(a, b, c, 0, 0, 0); }
; DI void gla_scan_item_lds(unsigned char* ldsb, int item, int tid, int wave, int lane) {
;     ...
;     for (int m = 0; m < 16; ++m) {
;         const unsigned char* buf = ldsb + (m & 1) * SC_BATCH_B;
; #pragma unroll
;         for (int s4 = 0; s4 < 4; ++s4) {
;             const int n = 4 * m + s4, cc = dir ? 63 - n : n; const unsigned char* sb = buf + s4 * SC_STEP_B;
;             u32x2 w_; w_.x = pk2(S[0], S[1]); w_.y = pk2(S[2], S[3]); *(u32x2*)(sp + (size_t)cc * 128 * 64) = w_;
;             const f32x4 dc = *(const f32x4*)(sb + dco);
;             S = S * dc;
;             S = mfma16(*(const bf16x8*)(sb + ao), *(const bf16x8*)(sb + bo), S);
;             S = mfma16(*(const bf16x8*)(sb + ao + 4096), *(const bf16x8*)(sb + bo + 2048), S);
;         }
.LBB0_732:
	s_bitcmp1_b32 s3, 0
	s_cselect_b32 s8, 0xc400, 0
	s_add_i32 s14, s8, 0
	v_add_u32_e32 v64, s14, v55
	v_add3_u32 v65, s14, v39, v41
	v_add3_u32 v66, s14, v49, v54
	ds_read_b128 v[68:71], v64 offset:12288
	ds_read_b128 v[72:75], v65
	ds_read_b128 v[76:79], v66 offset:8192
	ds_read_b128 v[80:83], v65 offset:4096
	ds_read_b128 v[84:87], v66 offset:10240
	ds_read_b128 v[88:91], v64 offset:24832
	ds_read_b128 v[92:95], v65 offset:12544
	ds_read_b128 v[96:99], v66 offset:20736
	ds_read_b128 v[100:103], v65 offset:16640
	ds_read_b128 v[104:107], v66 offset:22784
	ds_read_b128 v[108:111], v64 offset:37376
	ds_read_b128 v[112:115], v65 offset:25088
	ds_read_b128 v[116:119], v66 offset:33280
	ds_read_b128 v[120:123], v65 offset:29184
	ds_read_b128 v[124:127], v66 offset:35328
	ds_read_b128 v[128:131], v64 offset:49920
	ds_read_b128 v[132:135], v65 offset:37632
	ds_read_b128 v[136:139], v66 offset:45824
	ds_read_b128 v[140:143], v65 offset:41728
	ds_read_b128 v[144:147], v66 offset:47872
	s_add_i32 s8, s31, -11
	s_add_i32 s15, s50, 11
	s_and_b64 s[12:13], s[44:45], exec
	s_cselect_b32 s8, s8, s15
	s_lshl_b32 s8, s8, 14
	v_cvt_pk_bf16_f32 v50, v34, v35
	v_cvt_pk_bf16_f32 v51, v36, v37
	v_lshl_add_u64 v[52:53], v[46:47], 0, s[8:9]
	global_store_dwordx2 v[52:53], v[50:51], off
	s_waitcnt lgkmcnt(15)
	v_pk_mul_f32 v[36:37], v[36:37], v[70:71]
	v_pk_mul_f32 v[34:35], v[34:35], v[68:69]
	s_nop 1
	v_mfma_f32_16x16x32_bf16 v[34:37], v[72:75], v[76:79], v[34:37]
	v_mfma_f32_16x16x32_bf16 v[34:37], v[80:83], v[84:87], v[34:37]
	s_add_i32 s8, s31, -10
	s_add_i32 s15, s50, 10
	s_and_b64 s[12:13], s[44:45], exec
	s_cselect_b32 s8, s8, s15
	s_lshl_b32 s8, s8, 14
	s_nop 2
	v_cvt_pk_bf16_f32 v50, v34, v35
	v_cvt_pk_bf16_f32 v51, v36, v37
	v_lshl_add_u64 v[52:53], v[46:47], 0, s[8:9]
	global_store_dwordx2 v[52:53], v[50:51], off
	s_waitcnt lgkmcnt(10)
	v_pk_mul_f32 v[36:37], v[36:37], v[90:91]
	v_pk_mul_f32 v[34:35], v[34:35], v[88:89]
	s_nop 1
	v_mfma_f32_16x16x32_bf16 v[34:37], v[92:95], v[96:99], v[34:37]
	v_mfma_f32_16x16x32_bf16 v[34:37], v[100:103], v[104:107], v[34:37]
	s_add_i32 s8, s31, -9
	s_add_i32 s15, s50, 9
	s_and_b64 s[12:13], s[44:45], exec
	s_cselect_b32 s8, s8, s15
	s_lshl_b32 s8, s8, 14
	s_nop 2
	v_cvt_pk_bf16_f32 v50, v34, v35
	v_cvt_pk_bf16_f32 v51, v36, v37
	v_lshl_add_u64 v[52:53], v[46:47], 0, s[8:9]
	global_store_dwordx2 v[52:53], v[50:51], off
	s_waitcnt lgkmcnt(5)
	v_pk_mul_f32 v[36:37], v[36:37], v[110:111]
	v_pk_mul_f32 v[34:35], v[34:35], v[108:109]
	s_nop 1
	v_mfma_f32_16x16x32_bf16 v[34:37], v[112:115], v[116:119], v[34:37]
	v_mfma_f32_16x16x32_bf16 v[34:37], v[120:123], v[124:127], v[34:37]
	s_add_i32 s8, s31, -8
	s_add_i32 s15, s50, 8
	s_and_b64 s[12:13], s[44:45], exec
	s_cselect_b32 s8, s8, s15
	s_lshl_b32 s8, s8, 14
	s_nop 2
	v_cvt_pk_bf16_f32 v50, v34, v35
	v_cvt_pk_bf16_f32 v51, v36, v37
	v_lshl_add_u64 v[52:53], v[46:47], 0, s[8:9]
	global_store_dwordx2 v[52:53], v[50:51], off
	s_waitcnt lgkmcnt(0)
	v_pk_mul_f32 v[36:37], v[36:37], v[130:131]
	v_pk_mul_f32 v[34:35], v[34:35], v[128:129]
	s_nop 1
	v_mfma_f32_16x16x32_bf16 v[34:37], v[132:135], v[136:139], v[34:37]
	v_mfma_f32_16x16x32_bf16 v[34:37], v[140:143], v[144:147], v[34:37]
	s_cmpk_eq_i32 s31, 0x47
	s_cbranch_scc1 .LBB0_758
	s_andn2_b32 s8, 1, s3
	s_mul_i32 s8, s8, 0xc400
	v_add_u32_e32 v50, s8, v59
	s_waitcnt vmcnt(7)
	ds_write_b128 v50, v[18:21]
	s_and_saveexec_b64 s[12:13], vcc
	s_xor_b64 s[12:13], exec, s[12:13]
	s_cbranch_execz .LBB0_737
	s_and_saveexec_b64 s[14:15], s[42:43]
	ds_write_b128 v50, v[2:5] offset:8192
	s_or_b64 exec, exec, s[14:15]
